# GEMM K loops (FFN-in, w_in, resid): LDS-DMA addresses in SGPR-base + 32-bit VGPR offset form, no per-DMA 64-bit VALU add
# speedup vs baseline: 1.0052x; 1.0025x over previous
.LBB0_143:
	s_add_u32 s26, s16, 0xfffc0080
	s_addc_u32 s27, s17, -1
	s_add_i32 s34, 0, 0x10000
	s_cmp_eq_u32 s37, 12
	s_cselect_b32 s31, s9, s27
	s_cselect_b32 s30, s25, s26
	v_add_u32_e32 v138, s34, v141
	s_cselect_b32 s27, s7, s36
	s_cselect_b32 s26, s28, s29
	s_add_i32 s40, 0, 0x14000
	ds_read_b128 v[144:147], v138
	ds_read_b128 v[148:151], v138 offset:1024
	ds_read_b128 v[152:155], v138 offset:2048
	ds_read_b128 v[156:159], v138 offset:3072
	v_add_u32_e32 v138, s40, v141
	ds_read_b128 v[160:163], v138
	ds_read_b128 v[164:167], v138 offset:1024
	ds_read_b128 v[168:171], v138 offset:2048
	ds_read_b128 v[172:175], v138 offset:3072
	s_add_i32 m0, s53, 0xc000
	ds_read_b128 v[176:179], v143
	ds_read_b128 v[180:183], v143 offset:1024
	ds_read_b128 v[184:187], v143 offset:2048
	ds_read_b128 v[188:191], v143 offset:3072
	ds_read_b128 v[192:195], v143 offset:4096
	ds_read_b128 v[196:199], v143 offset:5120
	ds_read_b128 v[200:203], v143 offset:6144
	ds_read_b128 v[204:207], v143 offset:7168
	global_load_lds_dwordx4 v132, s[16:17]
	s_add_i32 m0, s53, 0xe000
	s_nop 0
	global_load_lds_dwordx4 v134, s[16:17]
	s_waitcnt vmcnt(8)
	s_waitcnt lgkmcnt(0)
	s_barrier
	s_setprio 1
	s_waitcnt lgkmcnt(0)
	v_mfma_f32_16x16x32_bf16 v[126:129], v[144:147], v[176:179], v[126:129]
	v_mfma_f32_16x16x32_bf16 v[126:129], v[148:151], v[180:183], v[126:129]
	v_mfma_f32_16x16x32_bf16 v[118:121], v[152:155], v[176:179], v[118:121]
	v_mfma_f32_16x16x32_bf16 v[118:121], v[156:159], v[180:183], v[118:121]
	v_mfma_f32_16x16x32_bf16 v[110:113], v[144:147], v[184:187], v[110:113]
	v_mfma_f32_16x16x32_bf16 v[110:113], v[148:151], v[188:191], v[110:113]
	v_mfma_f32_16x16x32_bf16 v[102:105], v[152:155], v[184:187], v[102:105]
	v_mfma_f32_16x16x32_bf16 v[102:105], v[156:159], v[188:191], v[102:105]
	v_mfma_f32_16x16x32_bf16 v[94:97], v[144:147], v[192:195], v[94:97]
	v_mfma_f32_16x16x32_bf16 v[94:97], v[148:151], v[196:199], v[94:97]
	v_mfma_f32_16x16x32_bf16 v[86:89], v[152:155], v[192:195], v[86:89]
	v_mfma_f32_16x16x32_bf16 v[86:89], v[156:159], v[196:199], v[86:89]
	v_mfma_f32_16x16x32_bf16 v[78:81], v[144:147], v[200:203], v[78:81]
	v_mfma_f32_16x16x32_bf16 v[78:81], v[148:151], v[204:207], v[78:81]
	v_mfma_f32_16x16x32_bf16 v[70:73], v[152:155], v[200:203], v[70:73]
	v_mfma_f32_16x16x32_bf16 v[70:73], v[156:159], v[204:207], v[70:73]
	s_setprio 0
	s_setprio 1
	v_mfma_f32_16x16x32_bf16 v[122:125], v[160:163], v[176:179], v[122:125]
	v_mfma_f32_16x16x32_bf16 v[122:125], v[164:167], v[180:183], v[122:125]
	v_mfma_f32_16x16x32_bf16 v[114:117], v[168:171], v[176:179], v[114:117]
	v_mfma_f32_16x16x32_bf16 v[114:117], v[172:175], v[180:183], v[114:117]
	v_mfma_f32_16x16x32_bf16 v[106:109], v[160:163], v[184:187], v[106:109]
	v_mfma_f32_16x16x32_bf16 v[106:109], v[164:167], v[188:191], v[106:109]
	v_mfma_f32_16x16x32_bf16 v[98:101], v[168:171], v[184:187], v[98:101]
	v_mfma_f32_16x16x32_bf16 v[98:101], v[172:175], v[188:191], v[98:101]
	v_mfma_f32_16x16x32_bf16 v[90:93], v[160:163], v[192:195], v[90:93]
	v_mfma_f32_16x16x32_bf16 v[90:93], v[164:167], v[196:199], v[90:93]
	v_mfma_f32_16x16x32_bf16 v[82:85], v[168:171], v[192:195], v[82:85]
	v_mfma_f32_16x16x32_bf16 v[82:85], v[172:175], v[196:199], v[82:85]
	s_setprio 3
	s_barrier
	v_mfma_f32_16x16x32_bf16 v[74:77], v[160:163], v[200:203], v[74:77]
	v_mfma_f32_16x16x32_bf16 v[74:77], v[164:167], v[204:207], v[74:77]
	v_mfma_f32_16x16x32_bf16 v[66:69], v[168:171], v[200:203], v[66:69]
	v_mfma_f32_16x16x32_bf16 v[66:69], v[172:175], v[204:207], v[66:69]
	s_setprio 0
	s_add_i32 s34, s34, s47
	s_mov_b32 m0, s34
	ds_read_b128 v[176:179], v143 offset:16384
	ds_read_b128 v[180:183], v143 offset:17408
	ds_read_b128 v[184:187], v143 offset:18432
	ds_read_b128 v[188:191], v143 offset:19456
	ds_read_b128 v[192:195], v143 offset:20480
	ds_read_b128 v[196:199], v143 offset:21504
	ds_read_b128 v[200:203], v143 offset:22528
	ds_read_b128 v[204:207], v143 offset:23552
	global_load_lds_dwordx4 v0, s[26:27]
	s_add_i32 m0, s34, 0x2000
	s_add_u32 s34, s26, 0x40000
	s_addc_u32 s35, s27, 0
	s_add_i32 s40, s40, s47
	global_load_lds_dwordx4 v130, s[26:27]
	s_mov_b32 m0, s40
	s_nop 0
	global_load_lds_dwordx4 v0, s[34:35]
	s_add_i32 m0, s40, 0x2000
	s_nop 0
	global_load_lds_dwordx4 v130, s[34:35]
	s_add_u32 s100, s30, s22
	s_addc_u32 s101, s31, s23
	s_mov_b32 m0, s53
	s_nop 0
	global_load_lds_dwordx4 v0, s[30:31]
	s_mov_b32 m0, s64
	s_nop 0
	global_load_lds_dwordx4 v130, s[30:31]
	s_waitcnt vmcnt(8)
	s_waitcnt lgkmcnt(0)
	s_barrier
	s_setprio 1
	s_waitcnt lgkmcnt(0)
	v_mfma_f32_16x16x32_bf16 v[62:65], v[144:147], v[176:179], v[62:65]
	v_mfma_f32_16x16x32_bf16 v[62:65], v[148:151], v[180:183], v[62:65]
	v_mfma_f32_16x16x32_bf16 v[54:57], v[152:155], v[176:179], v[54:57]
	v_mfma_f32_16x16x32_bf16 v[54:57], v[156:159], v[180:183], v[54:57]
	v_mfma_f32_16x16x32_bf16 v[46:49], v[144:147], v[184:187], v[46:49]
	v_mfma_f32_16x16x32_bf16 v[46:49], v[148:151], v[188:191], v[46:49]
	v_mfma_f32_16x16x32_bf16 v[38:41], v[152:155], v[184:187], v[38:41]
	v_mfma_f32_16x16x32_bf16 v[38:41], v[156:159], v[188:191], v[38:41]
	v_mfma_f32_16x16x32_bf16 v[30:33], v[144:147], v[192:195], v[30:33]
	v_mfma_f32_16x16x32_bf16 v[30:33], v[148:151], v[196:199], v[30:33]
	v_mfma_f32_16x16x32_bf16 v[22:25], v[152:155], v[192:195], v[22:25]
	v_mfma_f32_16x16x32_bf16 v[22:25], v[156:159], v[196:199], v[22:25]
	v_mfma_f32_16x16x32_bf16 v[14:17], v[144:147], v[200:203], v[14:17]
	v_mfma_f32_16x16x32_bf16 v[14:17], v[148:151], v[204:207], v[14:17]
	v_mfma_f32_16x16x32_bf16 v[6:9], v[152:155], v[200:203], v[6:9]
	v_mfma_f32_16x16x32_bf16 v[6:9], v[156:159], v[204:207], v[6:9]
	s_setprio 0
	s_setprio 1
	v_mfma_f32_16x16x32_bf16 v[58:61], v[160:163], v[176:179], v[58:61]
	v_mfma_f32_16x16x32_bf16 v[58:61], v[164:167], v[180:183], v[58:61]
	v_mfma_f32_16x16x32_bf16 v[50:53], v[168:171], v[176:179], v[50:53]
	v_mfma_f32_16x16x32_bf16 v[50:53], v[172:175], v[180:183], v[50:53]
	v_mfma_f32_16x16x32_bf16 v[42:45], v[160:163], v[184:187], v[42:45]
	v_mfma_f32_16x16x32_bf16 v[42:45], v[164:167], v[188:191], v[42:45]
	v_mfma_f32_16x16x32_bf16 v[34:37], v[168:171], v[184:187], v[34:37]
	v_mfma_f32_16x16x32_bf16 v[34:37], v[172:175], v[188:191], v[34:37]
	v_mfma_f32_16x16x32_bf16 v[26:29], v[160:163], v[192:195], v[26:29]
	v_mfma_f32_16x16x32_bf16 v[26:29], v[164:167], v[196:199], v[26:29]
	v_mfma_f32_16x16x32_bf16 v[18:21], v[168:171], v[192:195], v[18:21]
	v_mfma_f32_16x16x32_bf16 v[18:21], v[172:175], v[196:199], v[18:21]
	s_setprio 3
	s_barrier
	v_mfma_f32_16x16x32_bf16 v[10:13], v[160:163], v[200:203], v[10:13]
	v_mfma_f32_16x16x32_bf16 v[10:13], v[164:167], v[204:207], v[10:13]
	v_mfma_f32_16x16x32_bf16 v[2:5], v[168:171], v[200:203], v[2:5]
	v_mfma_f32_16x16x32_bf16 v[2:5], v[172:175], v[204:207], v[2:5]
	s_setprio 0
	s_add_i32 s34, 0, 0x18000
	s_add_i32 s35, 0, 0x1c000
	v_add_u32_e32 v156, s34, v141
	v_add_u32_e32 v172, s35, v141
	ds_read_b128 v[144:147], v156
	ds_read_b128 v[148:151], v156 offset:1024
	ds_read_b128 v[152:155], v156 offset:2048
	ds_read_b128 v[156:159], v156 offset:3072
	ds_read_b128 v[160:163], v172
	ds_read_b128 v[164:167], v172 offset:1024
	ds_read_b128 v[168:171], v172 offset:2048
	ds_read_b128 v[172:175], v172 offset:3072
	s_add_u32 s30, s30, 0x40000
	s_addc_u32 s31, s31, 0
	s_mov_b32 m0, s65
	ds_read_b128 v[176:179], v143 offset:32768
	ds_read_b128 v[180:183], v143 offset:33792
	ds_read_b128 v[184:187], v143 offset:34816
	ds_read_b128 v[188:191], v143 offset:35840
	ds_read_b128 v[192:195], v143 offset:36864
	ds_read_b128 v[196:199], v143 offset:37888
	ds_read_b128 v[200:203], v143 offset:38912
	ds_read_b128 v[204:207], v143 offset:39936
	global_load_lds_dwordx4 v0, s[30:31]
	s_mov_b32 m0, s68
	s_nop 0
	global_load_lds_dwordx4 v130, s[30:31]
	s_waitcnt vmcnt(8)
	s_waitcnt lgkmcnt(0)
	s_barrier
	s_setprio 1
	s_waitcnt lgkmcnt(0)
	v_mfma_f32_16x16x32_bf16 v[126:129], v[144:147], v[176:179], v[126:129]
	v_mfma_f32_16x16x32_bf16 v[126:129], v[148:151], v[180:183], v[126:129]
	v_mfma_f32_16x16x32_bf16 v[118:121], v[152:155], v[176:179], v[118:121]
	v_mfma_f32_16x16x32_bf16 v[118:121], v[156:159], v[180:183], v[118:121]
	v_mfma_f32_16x16x32_bf16 v[110:113], v[144:147], v[184:187], v[110:113]
	v_mfma_f32_16x16x32_bf16 v[110:113], v[148:151], v[188:191], v[110:113]
	v_mfma_f32_16x16x32_bf16 v[102:105], v[152:155], v[184:187], v[102:105]
	v_mfma_f32_16x16x32_bf16 v[102:105], v[156:159], v[188:191], v[102:105]
	v_mfma_f32_16x16x32_bf16 v[94:97], v[144:147], v[192:195], v[94:97]
	v_mfma_f32_16x16x32_bf16 v[94:97], v[148:151], v[196:199], v[94:97]
	v_mfma_f32_16x16x32_bf16 v[86:89], v[152:155], v[192:195], v[86:89]
	v_mfma_f32_16x16x32_bf16 v[86:89], v[156:159], v[196:199], v[86:89]
	v_mfma_f32_16x16x32_bf16 v[78:81], v[144:147], v[200:203], v[78:81]
	v_mfma_f32_16x16x32_bf16 v[78:81], v[148:151], v[204:207], v[78:81]
	v_mfma_f32_16x16x32_bf16 v[70:73], v[152:155], v[200:203], v[70:73]
	v_mfma_f32_16x16x32_bf16 v[70:73], v[156:159], v[204:207], v[70:73]
	s_setprio 0
	s_setprio 1
	v_mfma_f32_16x16x32_bf16 v[122:125], v[160:163], v[176:179], v[122:125]
	v_mfma_f32_16x16x32_bf16 v[122:125], v[164:167], v[180:183], v[122:125]
	v_mfma_f32_16x16x32_bf16 v[114:117], v[168:171], v[176:179], v[114:117]
	v_mfma_f32_16x16x32_bf16 v[114:117], v[172:175], v[180:183], v[114:117]
	v_mfma_f32_16x16x32_bf16 v[106:109], v[160:163], v[184:187], v[106:109]
	v_mfma_f32_16x16x32_bf16 v[106:109], v[164:167], v[188:191], v[106:109]
	v_mfma_f32_16x16x32_bf16 v[98:101], v[168:171], v[184:187], v[98:101]
	v_mfma_f32_16x16x32_bf16 v[98:101], v[172:175], v[188:191], v[98:101]
	v_mfma_f32_16x16x32_bf16 v[90:93], v[160:163], v[192:195], v[90:93]
	v_mfma_f32_16x16x32_bf16 v[90:93], v[164:167], v[196:199], v[90:93]
	v_mfma_f32_16x16x32_bf16 v[82:85], v[168:171], v[192:195], v[82:85]
	v_mfma_f32_16x16x32_bf16 v[82:85], v[172:175], v[196:199], v[82:85]
	s_setprio 3
	s_barrier
	v_mfma_f32_16x16x32_bf16 v[74:77], v[160:163], v[200:203], v[74:77]
	v_mfma_f32_16x16x32_bf16 v[74:77], v[164:167], v[204:207], v[74:77]
	v_mfma_f32_16x16x32_bf16 v[66:69], v[168:171], v[200:203], v[66:69]
	v_mfma_f32_16x16x32_bf16 v[66:69], v[172:175], v[204:207], v[66:69]
	s_setprio 0
	s_add_i32 s30, s34, s47
	s_add_u32 s98, s26, s22
	s_addc_u32 s99, s27, s23
	s_mov_b32 m0, s30
	ds_read_b128 v[176:179], v143 offset:49152
	ds_read_b128 v[180:183], v143 offset:50176
	ds_read_b128 v[184:187], v143 offset:51200
	ds_read_b128 v[188:191], v143 offset:52224
	ds_read_b128 v[192:195], v143 offset:53248
	ds_read_b128 v[196:199], v143 offset:54272
	ds_read_b128 v[200:203], v143 offset:55296
	ds_read_b128 v[204:207], v143 offset:56320
	global_load_lds_dwordx4 v0, s[98:99]
	s_add_i32 m0, s30, 0x2000
	s_add_u32 s26, s26, 0x40080
	s_addc_u32 s27, s27, 0
	s_add_i32 s30, s35, s47
	global_load_lds_dwordx4 v130, s[98:99]
	s_mov_b32 m0, s30
	s_nop 0
	global_load_lds_dwordx4 v0, s[26:27]
	s_add_i32 m0, s30, 0x2000
	s_nop 0
	global_load_lds_dwordx4 v130, s[26:27]
	s_mov_b32 m0, s69
	s_nop 0
	global_load_lds_dwordx4 v0, s[100:101]
	s_mov_b32 m0, s70
	s_nop 0
	global_load_lds_dwordx4 v130, s[100:101]
	s_waitcnt vmcnt(8)
	s_waitcnt lgkmcnt(0)
	s_barrier
	s_setprio 1
	s_waitcnt lgkmcnt(0)
	v_mfma_f32_16x16x32_bf16 v[62:65], v[144:147], v[176:179], v[62:65]
	v_mfma_f32_16x16x32_bf16 v[62:65], v[148:151], v[180:183], v[62:65]
	v_mfma_f32_16x16x32_bf16 v[54:57], v[152:155], v[176:179], v[54:57]
	v_mfma_f32_16x16x32_bf16 v[54:57], v[156:159], v[180:183], v[54:57]
	v_mfma_f32_16x16x32_bf16 v[46:49], v[144:147], v[184:187], v[46:49]
	v_mfma_f32_16x16x32_bf16 v[46:49], v[148:151], v[188:191], v[46:49]
	v_mfma_f32_16x16x32_bf16 v[38:41], v[152:155], v[184:187], v[38:41]
	v_mfma_f32_16x16x32_bf16 v[38:41], v[156:159], v[188:191], v[38:41]
	v_mfma_f32_16x16x32_bf16 v[30:33], v[144:147], v[192:195], v[30:33]
	v_mfma_f32_16x16x32_bf16 v[30:33], v[148:151], v[196:199], v[30:33]
	v_mfma_f32_16x16x32_bf16 v[22:25], v[152:155], v[192:195], v[22:25]
	v_mfma_f32_16x16x32_bf16 v[22:25], v[156:159], v[196:199], v[22:25]
	v_mfma_f32_16x16x32_bf16 v[14:17], v[144:147], v[200:203], v[14:17]
	v_mfma_f32_16x16x32_bf16 v[14:17], v[148:151], v[204:207], v[14:17]
	v_mfma_f32_16x16x32_bf16 v[6:9], v[152:155], v[200:203], v[6:9]
	v_mfma_f32_16x16x32_bf16 v[6:9], v[156:159], v[204:207], v[6:9]
	s_setprio 0
	s_setprio 1
	v_mfma_f32_16x16x32_bf16 v[58:61], v[160:163], v[176:179], v[58:61]
	v_mfma_f32_16x16x32_bf16 v[58:61], v[164:167], v[180:183], v[58:61]
	v_mfma_f32_16x16x32_bf16 v[50:53], v[168:171], v[176:179], v[50:53]
	v_mfma_f32_16x16x32_bf16 v[50:53], v[172:175], v[180:183], v[50:53]
	v_mfma_f32_16x16x32_bf16 v[42:45], v[160:163], v[184:187], v[42:45]
	v_mfma_f32_16x16x32_bf16 v[42:45], v[164:167], v[188:191], v[42:45]
	v_mfma_f32_16x16x32_bf16 v[34:37], v[168:171], v[184:187], v[34:37]
	v_mfma_f32_16x16x32_bf16 v[34:37], v[172:175], v[188:191], v[34:37]
	v_mfma_f32_16x16x32_bf16 v[26:29], v[160:163], v[192:195], v[26:29]
	v_mfma_f32_16x16x32_bf16 v[26:29], v[164:167], v[196:199], v[26:29]
	v_mfma_f32_16x16x32_bf16 v[18:21], v[168:171], v[192:195], v[18:21]
	v_mfma_f32_16x16x32_bf16 v[18:21], v[172:175], v[196:199], v[18:21]
	s_setprio 3
	s_barrier
	v_mfma_f32_16x16x32_bf16 v[10:13], v[160:163], v[200:203], v[10:13]
	v_mfma_f32_16x16x32_bf16 v[10:13], v[164:167], v[204:207], v[10:13]
	v_mfma_f32_16x16x32_bf16 v[2:5], v[168:171], v[200:203], v[2:5]
	v_mfma_f32_16x16x32_bf16 v[2:5], v[172:175], v[204:207], v[2:5]
	s_setprio 0
	s_add_i32 s37, s37, 2
	s_add_u32 s16, s16, 0x100
	s_addc_u32 s17, s17, 0
	s_add_u32 s29, s29, 0x100
	s_addc_u32 s36, s36, 0
	s_cmp_gt_u32 s37, 13
	s_cbranch_scc0 .LBB0_143
	s_and_b64 vcc, exec, s[2:3]
	s_cbranch_vccz .LBB0_146
	s_barrier

.LBB0_233:
	s_add_u32 s4, s0, 0xfffc0080
	s_addc_u32 s5, s1, -1
	s_add_i32 s18, 0, 0x10000
	s_cmp_eq_u32 s17, 12
	s_cselect_b32 s9, s3, s5
	s_cselect_b32 s8, s11, s4
	v_add_u32_e32 v0, s18, v191
	s_cselect_b32 s5, s12, s15
	s_cselect_b32 s4, s13, s14
	s_add_i32 s25, 0, 0x14000
	ds_read_b128 v[2:5], v0
	ds_read_b128 v[6:9], v0 offset:1024
	ds_read_b128 v[10:13], v0 offset:2048
	ds_read_b128 v[14:17], v0 offset:3072
	v_add_u32_e32 v0, s25, v191
	ds_read_b128 v[146:149], v0
	ds_read_b128 v[150:153], v0 offset:1024
	ds_read_b128 v[154:157], v0 offset:2048
	ds_read_b128 v[158:161], v0 offset:3072
	s_add_i32 m0, s65, 0xc000
	ds_read_b128 v[162:165], v200
	ds_read_b128 v[166:169], v200 offset:1024
	ds_read_b128 v[182:185], v200 offset:2048
	ds_read_b128 v[186:189], v200 offset:3072
	ds_read_b128 v[202:205], v200 offset:4096
	ds_read_b128 v[206:209], v200 offset:5120
	ds_read_b128 v[222:225], v200 offset:6144
	ds_read_b128 v[226:229], v200 offset:7168
	global_load_lds_dwordx4 v178, s[0:1]
	s_add_i32 m0, s65, 0xe000
	s_nop 0
	global_load_lds_dwordx4 v180, s[0:1]
	s_waitcnt vmcnt(8)
	s_waitcnt lgkmcnt(0)
	s_barrier
	s_setprio 1
	s_waitcnt lgkmcnt(0)
	v_mfma_f32_16x16x32_bf16 v[142:145], v[2:5], v[162:165], v[142:145]
	v_mfma_f32_16x16x32_bf16 v[142:145], v[6:9], v[166:169], v[142:145]
	v_mfma_f32_16x16x32_bf16 v[138:141], v[10:13], v[162:165], v[138:141]
	v_mfma_f32_16x16x32_bf16 v[138:141], v[14:17], v[166:169], v[138:141]
	v_mfma_f32_16x16x32_bf16 v[134:137], v[2:5], v[182:185], v[134:137]
	v_mfma_f32_16x16x32_bf16 v[134:137], v[6:9], v[186:189], v[134:137]
	v_mfma_f32_16x16x32_bf16 v[126:129], v[10:13], v[182:185], v[126:129]
	v_mfma_f32_16x16x32_bf16 v[126:129], v[14:17], v[186:189], v[126:129]
	v_mfma_f32_16x16x32_bf16 v[118:121], v[2:5], v[202:205], v[118:121]
	v_mfma_f32_16x16x32_bf16 v[118:121], v[6:9], v[206:209], v[118:121]
	v_mfma_f32_16x16x32_bf16 v[110:113], v[10:13], v[202:205], v[110:113]
	v_mfma_f32_16x16x32_bf16 v[110:113], v[14:17], v[206:209], v[110:113]
	v_mfma_f32_16x16x32_bf16 v[102:105], v[2:5], v[222:225], v[102:105]
	v_mfma_f32_16x16x32_bf16 v[102:105], v[6:9], v[226:229], v[102:105]
	v_mfma_f32_16x16x32_bf16 v[94:97], v[10:13], v[222:225], v[94:97]
	v_mfma_f32_16x16x32_bf16 v[94:97], v[14:17], v[226:229], v[94:97]
	s_setprio 0
	s_setprio 1
	v_mfma_f32_16x16x32_bf16 v[130:133], v[146:149], v[162:165], v[130:133]
	v_mfma_f32_16x16x32_bf16 v[130:133], v[150:153], v[166:169], v[130:133]
	v_mfma_f32_16x16x32_bf16 v[122:125], v[154:157], v[162:165], v[122:125]
	v_mfma_f32_16x16x32_bf16 v[122:125], v[158:161], v[166:169], v[122:125]
	v_mfma_f32_16x16x32_bf16 v[114:117], v[146:149], v[182:185], v[114:117]
	v_mfma_f32_16x16x32_bf16 v[114:117], v[150:153], v[186:189], v[114:117]
	v_mfma_f32_16x16x32_bf16 v[106:109], v[154:157], v[182:185], v[106:109]
	v_mfma_f32_16x16x32_bf16 v[106:109], v[158:161], v[186:189], v[106:109]
	v_mfma_f32_16x16x32_bf16 v[98:101], v[146:149], v[202:205], v[98:101]
	v_mfma_f32_16x16x32_bf16 v[98:101], v[150:153], v[206:209], v[98:101]
	v_mfma_f32_16x16x32_bf16 v[90:93], v[154:157], v[202:205], v[90:93]
	v_mfma_f32_16x16x32_bf16 v[90:93], v[158:161], v[206:209], v[90:93]
	s_setprio 3
	s_barrier
	v_mfma_f32_16x16x32_bf16 v[86:89], v[146:149], v[222:225], v[86:89]
	v_mfma_f32_16x16x32_bf16 v[86:89], v[150:153], v[226:229], v[86:89]
	v_mfma_f32_16x16x32_bf16 v[82:85], v[154:157], v[222:225], v[82:85]
	v_mfma_f32_16x16x32_bf16 v[82:85], v[158:161], v[226:229], v[82:85]
	s_setprio 0
	s_add_i32 s18, s18, s64
	s_mov_b32 m0, s18
	ds_read_b128 v[162:165], v200 offset:16384
	ds_read_b128 v[166:169], v200 offset:17408
	ds_read_b128 v[182:185], v200 offset:18432
	ds_read_b128 v[186:189], v200 offset:19456
	ds_read_b128 v[202:205], v200 offset:20480
	ds_read_b128 v[206:209], v200 offset:21504
	ds_read_b128 v[222:225], v200 offset:22528
	ds_read_b128 v[226:229], v200 offset:23552
	global_load_lds_dwordx4 v172, s[4:5]
	s_add_i32 m0, s18, 0x2000
	s_add_u32 s18, s4, 0x40000
	s_addc_u32 s19, s5, 0
	s_add_i32 s25, s25, s64
	global_load_lds_dwordx4 v170, s[4:5]
	s_mov_b32 m0, s25
	s_nop 0
	global_load_lds_dwordx4 v172, s[18:19]
	s_add_i32 m0, s25, 0x2000
	s_nop 0
	global_load_lds_dwordx4 v170, s[18:19]
	s_add_u32 s100, s8, s22
	s_addc_u32 s101, s9, s23
	s_mov_b32 m0, s65
	s_nop 0
	global_load_lds_dwordx4 v172, s[8:9]
	s_mov_b32 m0, s68
	s_nop 0
	global_load_lds_dwordx4 v170, s[8:9]
	s_waitcnt vmcnt(8)
	s_waitcnt lgkmcnt(0)
	s_barrier
	s_setprio 1
	s_waitcnt lgkmcnt(0)
	v_mfma_f32_16x16x32_bf16 v[78:81], v[2:5], v[162:165], v[78:81]
	v_mfma_f32_16x16x32_bf16 v[74:77], v[10:13], v[162:165], v[74:77]
	v_mfma_f32_16x16x32_bf16 v[70:73], v[2:5], v[182:185], v[70:73]
	v_mfma_f32_16x16x32_bf16 v[62:65], v[10:13], v[182:185], v[62:65]
	v_mfma_f32_16x16x32_bf16 v[54:57], v[2:5], v[202:205], v[54:57]
	v_mfma_f32_16x16x32_bf16 v[46:49], v[10:13], v[202:205], v[46:49]
	v_mfma_f32_16x16x32_bf16 v[2:5], v[2:5], v[222:225], v[38:41]
	v_mfma_f32_16x16x32_bf16 v[78:81], v[6:9], v[166:169], v[78:81]
	v_mfma_f32_16x16x32_bf16 v[74:77], v[14:17], v[166:169], v[74:77]
	v_mfma_f32_16x16x32_bf16 v[70:73], v[6:9], v[186:189], v[70:73]
	v_mfma_f32_16x16x32_bf16 v[62:65], v[14:17], v[186:189], v[62:65]
	v_mfma_f32_16x16x32_bf16 v[54:57], v[6:9], v[206:209], v[54:57]
	v_mfma_f32_16x16x32_bf16 v[46:49], v[14:17], v[206:209], v[46:49]
	v_mfma_f32_16x16x32_bf16 v[2:5], v[6:9], v[226:229], v[2:5]
	v_mfma_f32_16x16x32_bf16 v[6:9], v[10:13], v[222:225], v[30:33]
	v_mfma_f32_16x16x32_bf16 v[6:9], v[14:17], v[226:229], v[6:9]
	s_setprio 0
	s_setprio 1
	v_mfma_f32_16x16x32_bf16 v[30:33], v[146:149], v[182:185], v[50:53]
	v_mfma_f32_16x16x32_bf16 v[50:53], v[150:153], v[186:189], v[30:33]
	v_mfma_f32_16x16x32_bf16 v[30:33], v[154:157], v[182:185], v[42:45]
	v_mfma_f32_16x16x32_bf16 v[42:45], v[158:161], v[186:189], v[30:33]
	v_mfma_f32_16x16x32_bf16 v[30:33], v[146:149], v[202:205], v[34:37]
	v_mfma_f32_16x16x32_bf16 v[26:29], v[154:157], v[202:205], v[26:29]
	v_mfma_f32_16x16x32_bf16 v[22:25], v[146:149], v[222:225], v[22:25]
	v_mfma_f32_16x16x32_bf16 v[18:21], v[154:157], v[222:225], v[18:21]
	v_mfma_f32_16x16x32_bf16 v[10:13], v[146:149], v[162:165], v[66:69]
	v_mfma_f32_16x16x32_bf16 v[14:17], v[154:157], v[162:165], v[58:61]
	v_mfma_f32_16x16x32_bf16 v[34:37], v[150:153], v[206:209], v[30:33]
	v_mfma_f32_16x16x32_bf16 v[26:29], v[158:161], v[206:209], v[26:29]
	s_setprio 3
	s_barrier
	v_mfma_f32_16x16x32_bf16 v[22:25], v[150:153], v[226:229], v[22:25]
	v_mfma_f32_16x16x32_bf16 v[18:21], v[158:161], v[226:229], v[18:21]
	v_mfma_f32_16x16x32_bf16 v[10:13], v[150:153], v[166:169], v[10:13]
	v_mfma_f32_16x16x32_bf16 v[14:17], v[158:161], v[166:169], v[14:17]
	s_setprio 0
	s_add_i32 s18, 0, 0x18000
	v_add_u32_e32 v0, s18, v191
	s_add_i32 s19, 0, 0x1c000
	ds_read_b128 v[30:33], v0
	ds_read_b128 v[38:41], v0 offset:1024
	ds_read_b128 v[58:61], v0 offset:2048
	ds_read_b128 v[66:69], v0 offset:3072
	v_add_u32_e32 v0, s19, v191
	ds_read_b128 v[146:149], v0
	ds_read_b128 v[150:153], v0 offset:1024
	ds_read_b128 v[154:157], v0 offset:2048
	ds_read_b128 v[158:161], v0 offset:3072
	s_add_u32 s8, s8, 0x40000
	s_addc_u32 s9, s9, 0
	s_mov_b32 m0, s69
	ds_read_b128 v[162:165], v200 offset:32768
	ds_read_b128 v[166:169], v200 offset:33792
	ds_read_b128 v[182:185], v200 offset:34816
	ds_read_b128 v[186:189], v200 offset:35840
	ds_read_b128 v[202:205], v200 offset:36864
	ds_read_b128 v[206:209], v200 offset:37888
	ds_read_b128 v[222:225], v200 offset:38912
	ds_read_b128 v[226:229], v200 offset:39936
	global_load_lds_dwordx4 v172, s[8:9]
	s_mov_b32 m0, s70
	s_nop 0
	global_load_lds_dwordx4 v170, s[8:9]
	s_waitcnt vmcnt(8)
	s_waitcnt lgkmcnt(0)
	s_barrier
	s_setprio 1
	s_waitcnt lgkmcnt(0)
	v_mfma_f32_16x16x32_bf16 v[142:145], v[30:33], v[162:165], v[142:145]
	v_mfma_f32_16x16x32_bf16 v[142:145], v[38:41], v[166:169], v[142:145]
	v_mfma_f32_16x16x32_bf16 v[138:141], v[58:61], v[162:165], v[138:141]
	v_mfma_f32_16x16x32_bf16 v[138:141], v[66:69], v[166:169], v[138:141]
	v_mfma_f32_16x16x32_bf16 v[134:137], v[30:33], v[182:185], v[134:137]
	v_mfma_f32_16x16x32_bf16 v[134:137], v[38:41], v[186:189], v[134:137]
	v_mfma_f32_16x16x32_bf16 v[126:129], v[58:61], v[182:185], v[126:129]
	v_mfma_f32_16x16x32_bf16 v[126:129], v[66:69], v[186:189], v[126:129]
	v_mfma_f32_16x16x32_bf16 v[118:121], v[30:33], v[202:205], v[118:121]
	v_mfma_f32_16x16x32_bf16 v[118:121], v[38:41], v[206:209], v[118:121]
	v_mfma_f32_16x16x32_bf16 v[110:113], v[58:61], v[202:205], v[110:113]
	v_mfma_f32_16x16x32_bf16 v[110:113], v[66:69], v[206:209], v[110:113]
	v_mfma_f32_16x16x32_bf16 v[102:105], v[30:33], v[222:225], v[102:105]
	v_mfma_f32_16x16x32_bf16 v[102:105], v[38:41], v[226:229], v[102:105]
	v_mfma_f32_16x16x32_bf16 v[94:97], v[58:61], v[222:225], v[94:97]
	v_mfma_f32_16x16x32_bf16 v[94:97], v[66:69], v[226:229], v[94:97]
	s_setprio 0
	s_setprio 1
	v_mfma_f32_16x16x32_bf16 v[130:133], v[146:149], v[162:165], v[130:133]
	v_mfma_f32_16x16x32_bf16 v[130:133], v[150:153], v[166:169], v[130:133]
	v_mfma_f32_16x16x32_bf16 v[122:125], v[154:157], v[162:165], v[122:125]
	v_mfma_f32_16x16x32_bf16 v[122:125], v[158:161], v[166:169], v[122:125]
	v_mfma_f32_16x16x32_bf16 v[114:117], v[146:149], v[182:185], v[114:117]
	v_mfma_f32_16x16x32_bf16 v[114:117], v[150:153], v[186:189], v[114:117]
	v_mfma_f32_16x16x32_bf16 v[106:109], v[154:157], v[182:185], v[106:109]
	v_mfma_f32_16x16x32_bf16 v[106:109], v[158:161], v[186:189], v[106:109]
	v_mfma_f32_16x16x32_bf16 v[98:101], v[146:149], v[202:205], v[98:101]
	v_mfma_f32_16x16x32_bf16 v[98:101], v[150:153], v[206:209], v[98:101]
	v_mfma_f32_16x16x32_bf16 v[90:93], v[154:157], v[202:205], v[90:93]
	v_mfma_f32_16x16x32_bf16 v[90:93], v[158:161], v[206:209], v[90:93]
	s_setprio 3
	s_barrier
	v_mfma_f32_16x16x32_bf16 v[86:89], v[146:149], v[222:225], v[86:89]
	v_mfma_f32_16x16x32_bf16 v[86:89], v[150:153], v[226:229], v[86:89]
	v_mfma_f32_16x16x32_bf16 v[82:85], v[154:157], v[222:225], v[82:85]
	v_mfma_f32_16x16x32_bf16 v[82:85], v[158:161], v[226:229], v[82:85]
	s_setprio 0
	s_add_i32 s8, s18, s64
	s_add_u32 s98, s4, s22
	s_addc_u32 s99, s5, s23
	s_mov_b32 m0, s8
	ds_read_b128 v[162:165], v200 offset:49152
	ds_read_b128 v[166:169], v200 offset:50176
	ds_read_b128 v[182:185], v200 offset:51200
	ds_read_b128 v[186:189], v200 offset:52224
	ds_read_b128 v[202:205], v200 offset:53248
	ds_read_b128 v[206:209], v200 offset:54272
	ds_read_b128 v[222:225], v200 offset:55296
	ds_read_b128 v[226:229], v200 offset:56320
	global_load_lds_dwordx4 v172, s[98:99]
	s_add_i32 m0, s8, 0x2000
	s_add_u32 s4, s4, 0x40080
	s_addc_u32 s5, s5, 0
	s_add_i32 s8, s19, s64
	global_load_lds_dwordx4 v170, s[98:99]
	s_mov_b32 m0, s8
	s_nop 0
	global_load_lds_dwordx4 v172, s[4:5]
	s_add_i32 m0, s8, 0x2000
	s_nop 0
	global_load_lds_dwordx4 v170, s[4:5]
	s_mov_b32 m0, s94
	s_nop 0
	global_load_lds_dwordx4 v172, s[100:101]
	s_mov_b32 m0, s95
	s_nop 0
	global_load_lds_dwordx4 v170, s[100:101]
	s_waitcnt vmcnt(8)
	s_waitcnt lgkmcnt(0)
	s_barrier
	s_setprio 1
	s_waitcnt lgkmcnt(0)
	v_mfma_f32_16x16x32_bf16 v[78:81], v[30:33], v[162:165], v[78:81]
	v_mfma_f32_16x16x32_bf16 v[70:73], v[30:33], v[182:185], v[70:73]
	v_mfma_f32_16x16x32_bf16 v[54:57], v[30:33], v[202:205], v[54:57]
	v_mfma_f32_16x16x32_bf16 v[2:5], v[30:33], v[222:225], v[2:5]
	v_mfma_f32_16x16x32_bf16 v[78:81], v[38:41], v[166:169], v[78:81]
	v_mfma_f32_16x16x32_bf16 v[74:77], v[58:61], v[162:165], v[74:77]
	v_mfma_f32_16x16x32_bf16 v[70:73], v[38:41], v[186:189], v[70:73]
	v_mfma_f32_16x16x32_bf16 v[62:65], v[58:61], v[182:185], v[62:65]
	v_mfma_f32_16x16x32_bf16 v[54:57], v[38:41], v[206:209], v[54:57]
	v_mfma_f32_16x16x32_bf16 v[46:49], v[58:61], v[202:205], v[46:49]
	v_mfma_f32_16x16x32_bf16 v[38:41], v[38:41], v[226:229], v[2:5]
	v_mfma_f32_16x16x32_bf16 v[2:5], v[58:61], v[222:225], v[6:9]
	v_mfma_f32_16x16x32_bf16 v[74:77], v[66:69], v[166:169], v[74:77]
	v_mfma_f32_16x16x32_bf16 v[62:65], v[66:69], v[186:189], v[62:65]
	v_mfma_f32_16x16x32_bf16 v[46:49], v[66:69], v[206:209], v[46:49]
	v_mfma_f32_16x16x32_bf16 v[30:33], v[66:69], v[226:229], v[2:5]
	s_setprio 0
	s_setprio 1
	v_mfma_f32_16x16x32_bf16 v[2:5], v[146:149], v[162:165], v[10:13]
	v_mfma_f32_16x16x32_bf16 v[66:69], v[150:153], v[166:169], v[2:5]
	v_mfma_f32_16x16x32_bf16 v[2:5], v[154:157], v[162:165], v[14:17]
	v_mfma_f32_16x16x32_bf16 v[58:61], v[158:161], v[166:169], v[2:5]
	v_mfma_f32_16x16x32_bf16 v[2:5], v[146:149], v[182:185], v[50:53]
	v_mfma_f32_16x16x32_bf16 v[50:53], v[150:153], v[186:189], v[2:5]
	v_mfma_f32_16x16x32_bf16 v[2:5], v[154:157], v[182:185], v[42:45]
	v_mfma_f32_16x16x32_bf16 v[42:45], v[158:161], v[186:189], v[2:5]
	v_mfma_f32_16x16x32_bf16 v[2:5], v[146:149], v[202:205], v[34:37]
	v_mfma_f32_16x16x32_bf16 v[34:37], v[150:153], v[206:209], v[2:5]
	v_mfma_f32_16x16x32_bf16 v[2:5], v[154:157], v[202:205], v[26:29]
	v_mfma_f32_16x16x32_bf16 v[26:29], v[158:161], v[206:209], v[2:5]
	s_setprio 3
	s_barrier
	v_mfma_f32_16x16x32_bf16 v[2:5], v[146:149], v[222:225], v[22:25]
	v_mfma_f32_16x16x32_bf16 v[22:25], v[150:153], v[226:229], v[2:5]
	v_mfma_f32_16x16x32_bf16 v[2:5], v[154:157], v[222:225], v[18:21]
	v_mfma_f32_16x16x32_bf16 v[18:21], v[158:161], v[226:229], v[2:5]
	s_setprio 0
	s_add_i32 s17, s17, 2
	s_add_u32 s0, s0, 0x100
	s_addc_u32 s1, s1, 0
	s_add_u32 s14, s14, 0x100
	s_addc_u32 s15, s15, 0
	s_cmp_gt_u32 s17, 13
	s_cbranch_scc0 .LBB0_233
	s_and_b64 vcc, exec, s[78:79]
	s_cbranch_vccz .LBB0_236
	s_barrier

.LBB0_707:
	s_add_i32 s34, s68, 2
	s_add_u32 s35, s0, 0x80
	s_addc_u32 s69, s1, 0
	s_add_i32 s84, 0, 0x10000
	s_cmp_eq_u32 s96, s68
	s_cselect_b32 s69, s53, s69
	s_cselect_b32 s68, s52, s35
	s_cselect_b32 s89, s65, vcc_hi
	s_cselect_b32 s88, s64, vcc_lo
	s_add_i32 s35, 0, 0x14000
	v_add_u32_e32 v142, s84, v212
	v_add_u32_e32 v158, s35, v212
	ds_read_b128 v[130:133], v142
	ds_read_b128 v[134:137], v142 offset:1024
	ds_read_b128 v[138:141], v142 offset:2048
	ds_read_b128 v[142:145], v142 offset:3072
	ds_read_b128 v[146:149], v158
	ds_read_b128 v[150:153], v158 offset:1024
	ds_read_b128 v[154:157], v158 offset:2048
	ds_read_b128 v[158:161], v158 offset:3072
	v_lshl_add_u64 v[194:195], s[0:1], 0, v[224:225]
	s_add_i32 m0, s28, 0xc000
	ds_read_b128 v[162:165], v245
	ds_read_b128 v[166:169], v245 offset:1024
	ds_read_b128 v[170:173], v245 offset:2048
	ds_read_b128 v[174:177], v245 offset:3072
	ds_read_b128 v[178:181], v245 offset:4096
	ds_read_b128 v[182:185], v245 offset:5120
	ds_read_b128 v[186:189], v245 offset:6144
	ds_read_b128 v[190:193], v245 offset:7168
	global_load_lds_dwordx4 v[194:195], off
	v_lshl_add_u64 v[194:195], s[0:1], 0, v[226:227]
	s_add_i32 m0, s28, 0xe000
	s_nop 0
	global_load_lds_dwordx4 v[194:195], off
	s_waitcnt vmcnt(8)
	s_waitcnt lgkmcnt(0)
	s_barrier
	s_setprio 1
	s_waitcnt lgkmcnt(0)
	v_mfma_f32_16x16x32_bf16 v[126:129], v[130:133], v[162:165], v[126:129]
	v_mfma_f32_16x16x32_bf16 v[126:129], v[134:137], v[166:169], v[126:129]
	v_mfma_f32_16x16x32_bf16 v[122:125], v[138:141], v[162:165], v[122:125]
	v_mfma_f32_16x16x32_bf16 v[122:125], v[142:145], v[166:169], v[122:125]
	v_mfma_f32_16x16x32_bf16 v[114:117], v[130:133], v[170:173], v[114:117]
	v_mfma_f32_16x16x32_bf16 v[114:117], v[134:137], v[174:177], v[114:117]
	v_mfma_f32_16x16x32_bf16 v[106:109], v[138:141], v[170:173], v[106:109]
	v_mfma_f32_16x16x32_bf16 v[106:109], v[142:145], v[174:177], v[106:109]
	v_mfma_f32_16x16x32_bf16 v[98:101], v[130:133], v[178:181], v[98:101]
	v_mfma_f32_16x16x32_bf16 v[98:101], v[134:137], v[182:185], v[98:101]
	v_mfma_f32_16x16x32_bf16 v[90:93], v[138:141], v[178:181], v[90:93]
	v_mfma_f32_16x16x32_bf16 v[90:93], v[142:145], v[182:185], v[90:93]
	v_mfma_f32_16x16x32_bf16 v[82:85], v[130:133], v[186:189], v[82:85]
	v_mfma_f32_16x16x32_bf16 v[82:85], v[134:137], v[190:193], v[82:85]
	v_mfma_f32_16x16x32_bf16 v[74:77], v[138:141], v[186:189], v[74:77]
	v_mfma_f32_16x16x32_bf16 v[74:77], v[142:145], v[190:193], v[74:77]
	s_setprio 0
	s_setprio 1
	v_mfma_f32_16x16x32_bf16 v[118:121], v[146:149], v[162:165], v[118:121]
	v_mfma_f32_16x16x32_bf16 v[118:121], v[150:153], v[166:169], v[118:121]
	v_mfma_f32_16x16x32_bf16 v[110:113], v[154:157], v[162:165], v[110:113]
	v_mfma_f32_16x16x32_bf16 v[110:113], v[158:161], v[166:169], v[110:113]
	v_mfma_f32_16x16x32_bf16 v[102:105], v[146:149], v[170:173], v[102:105]
	v_mfma_f32_16x16x32_bf16 v[102:105], v[150:153], v[174:177], v[102:105]
	v_mfma_f32_16x16x32_bf16 v[94:97], v[154:157], v[170:173], v[94:97]
	v_mfma_f32_16x16x32_bf16 v[94:97], v[158:161], v[174:177], v[94:97]
	v_mfma_f32_16x16x32_bf16 v[86:89], v[146:149], v[178:181], v[86:89]
	v_mfma_f32_16x16x32_bf16 v[86:89], v[150:153], v[182:185], v[86:89]
	v_mfma_f32_16x16x32_bf16 v[78:81], v[154:157], v[178:181], v[78:81]
	v_mfma_f32_16x16x32_bf16 v[78:81], v[158:161], v[182:185], v[78:81]
	s_setprio 3
	s_barrier
	v_mfma_f32_16x16x32_bf16 v[70:73], v[146:149], v[186:189], v[70:73]
	v_mfma_f32_16x16x32_bf16 v[70:73], v[150:153], v[190:193], v[70:73]
	v_mfma_f32_16x16x32_bf16 v[66:69], v[154:157], v[186:189], v[66:69]
	v_mfma_f32_16x16x32_bf16 v[66:69], v[158:161], v[190:193], v[66:69]
	s_setprio 0
	s_add_i32 s84, s84, s19
	s_add_u32 s98, s88, s22
	s_addc_u32 s99, s89, s23
	s_mov_b32 m0, s84
	ds_read_b128 v[162:165], v245 offset:16384
	ds_read_b128 v[166:169], v245 offset:17408
	ds_read_b128 v[170:173], v245 offset:18432
	ds_read_b128 v[174:177], v245 offset:19456
	ds_read_b128 v[178:181], v245 offset:20480
	ds_read_b128 v[182:185], v245 offset:21504
	ds_read_b128 v[186:189], v245 offset:22528
	ds_read_b128 v[190:193], v245 offset:23552
	global_load_lds_dwordx4 v0, s[88:89]
	s_add_i32 m0, s84, 0x2000
	s_add_i32 s35, s35, s19
	global_load_lds_dwordx4 v222, s[88:89]
	s_add_u32 s88, s88, s2
	s_addc_u32 s89, s89, 0
	s_mov_b32 m0, s35
	s_nop 0
	global_load_lds_dwordx4 v0, s[88:89]
	s_add_i32 m0, s35, 0x2000
	s_add_u32 s100, s68, s22
	s_addc_u32 s101, s69, s23
	global_load_lds_dwordx4 v222, s[88:89]
	s_mov_b32 m0, s28
	s_nop 0
	global_load_lds_dwordx4 v0, s[68:69]
	s_mov_b32 m0, s29
	s_nop 0
	global_load_lds_dwordx4 v222, s[68:69]
	s_waitcnt vmcnt(8)
	s_waitcnt lgkmcnt(0)
	s_barrier
	s_setprio 1
	s_waitcnt lgkmcnt(0)
	v_mfma_f32_16x16x32_bf16 v[62:65], v[130:133], v[162:165], v[62:65]
	v_mfma_f32_16x16x32_bf16 v[62:65], v[134:137], v[166:169], v[62:65]
	v_mfma_f32_16x16x32_bf16 v[58:61], v[138:141], v[162:165], v[58:61]
	v_mfma_f32_16x16x32_bf16 v[58:61], v[142:145], v[166:169], v[58:61]
	v_mfma_f32_16x16x32_bf16 v[50:53], v[130:133], v[170:173], v[50:53]
	v_mfma_f32_16x16x32_bf16 v[50:53], v[134:137], v[174:177], v[50:53]
	v_mfma_f32_16x16x32_bf16 v[42:45], v[138:141], v[170:173], v[42:45]
	v_mfma_f32_16x16x32_bf16 v[42:45], v[142:145], v[174:177], v[42:45]
	v_mfma_f32_16x16x32_bf16 v[34:37], v[130:133], v[178:181], v[34:37]
	v_mfma_f32_16x16x32_bf16 v[34:37], v[134:137], v[182:185], v[34:37]
	v_mfma_f32_16x16x32_bf16 v[26:29], v[138:141], v[178:181], v[26:29]
	v_mfma_f32_16x16x32_bf16 v[26:29], v[142:145], v[182:185], v[26:29]
	v_mfma_f32_16x16x32_bf16 v[18:21], v[130:133], v[186:189], v[18:21]
	v_mfma_f32_16x16x32_bf16 v[18:21], v[134:137], v[190:193], v[18:21]
	v_mfma_f32_16x16x32_bf16 v[10:13], v[138:141], v[186:189], v[10:13]
	v_mfma_f32_16x16x32_bf16 v[10:13], v[142:145], v[190:193], v[10:13]
	s_setprio 0
	s_setprio 1
	v_mfma_f32_16x16x32_bf16 v[54:57], v[146:149], v[162:165], v[54:57]
	v_mfma_f32_16x16x32_bf16 v[54:57], v[150:153], v[166:169], v[54:57]
	v_mfma_f32_16x16x32_bf16 v[46:49], v[154:157], v[162:165], v[46:49]
	v_mfma_f32_16x16x32_bf16 v[46:49], v[158:161], v[166:169], v[46:49]
	v_mfma_f32_16x16x32_bf16 v[38:41], v[146:149], v[170:173], v[38:41]
	v_mfma_f32_16x16x32_bf16 v[38:41], v[150:153], v[174:177], v[38:41]
	v_mfma_f32_16x16x32_bf16 v[30:33], v[154:157], v[170:173], v[30:33]
	v_mfma_f32_16x16x32_bf16 v[30:33], v[158:161], v[174:177], v[30:33]
	v_mfma_f32_16x16x32_bf16 v[22:25], v[146:149], v[178:181], v[22:25]
	v_mfma_f32_16x16x32_bf16 v[22:25], v[150:153], v[182:185], v[22:25]
	v_mfma_f32_16x16x32_bf16 v[14:17], v[154:157], v[178:181], v[14:17]
	v_mfma_f32_16x16x32_bf16 v[14:17], v[158:161], v[182:185], v[14:17]
	s_setprio 3
	s_barrier
	v_mfma_f32_16x16x32_bf16 v[6:9], v[146:149], v[186:189], v[6:9]
	v_mfma_f32_16x16x32_bf16 v[6:9], v[150:153], v[190:193], v[6:9]
	v_mfma_f32_16x16x32_bf16 v[2:5], v[154:157], v[186:189], v[2:5]
	v_mfma_f32_16x16x32_bf16 v[2:5], v[158:161], v[190:193], v[2:5]
	s_setprio 0
	s_add_i32 s35, 0, 0x18000
	s_add_i32 s84, 0, 0x1c000
	v_add_u32_e32 v142, s35, v212
	v_add_u32_e32 v158, s84, v212
	ds_read_b128 v[130:133], v142
	ds_read_b128 v[134:137], v142 offset:1024
	ds_read_b128 v[138:141], v142 offset:2048
	ds_read_b128 v[142:145], v142 offset:3072
	ds_read_b128 v[146:149], v158
	ds_read_b128 v[150:153], v158 offset:1024
	ds_read_b128 v[154:157], v158 offset:2048
	ds_read_b128 v[158:161], v158 offset:3072
	s_add_u32 s68, s68, s2
	s_addc_u32 s69, s69, 0
	s_mov_b32 m0, s25
	ds_read_b128 v[162:165], v245 offset:32768
	ds_read_b128 v[166:169], v245 offset:33792
	ds_read_b128 v[170:173], v245 offset:34816
	ds_read_b128 v[174:177], v245 offset:35840
	ds_read_b128 v[178:181], v245 offset:36864
	ds_read_b128 v[182:185], v245 offset:37888
	ds_read_b128 v[186:189], v245 offset:38912
	ds_read_b128 v[190:193], v245 offset:39936
	global_load_lds_dwordx4 v0, s[68:69]
	s_mov_b32 m0, s36
	s_nop 0
	global_load_lds_dwordx4 v222, s[68:69]
	s_waitcnt vmcnt(8)
	s_waitcnt lgkmcnt(0)
	s_barrier
	s_setprio 1
	s_waitcnt lgkmcnt(0)
	v_mfma_f32_16x16x32_bf16 v[126:129], v[130:133], v[162:165], v[126:129]
	v_mfma_f32_16x16x32_bf16 v[126:129], v[134:137], v[166:169], v[126:129]
	v_mfma_f32_16x16x32_bf16 v[122:125], v[138:141], v[162:165], v[122:125]
	v_mfma_f32_16x16x32_bf16 v[122:125], v[142:145], v[166:169], v[122:125]
	v_mfma_f32_16x16x32_bf16 v[114:117], v[130:133], v[170:173], v[114:117]
	v_mfma_f32_16x16x32_bf16 v[114:117], v[134:137], v[174:177], v[114:117]
	v_mfma_f32_16x16x32_bf16 v[106:109], v[138:141], v[170:173], v[106:109]
	v_mfma_f32_16x16x32_bf16 v[106:109], v[142:145], v[174:177], v[106:109]
	v_mfma_f32_16x16x32_bf16 v[98:101], v[130:133], v[178:181], v[98:101]
	v_mfma_f32_16x16x32_bf16 v[98:101], v[134:137], v[182:185], v[98:101]
	v_mfma_f32_16x16x32_bf16 v[90:93], v[138:141], v[178:181], v[90:93]
	v_mfma_f32_16x16x32_bf16 v[90:93], v[142:145], v[182:185], v[90:93]
	v_mfma_f32_16x16x32_bf16 v[82:85], v[130:133], v[186:189], v[82:85]
	v_mfma_f32_16x16x32_bf16 v[82:85], v[134:137], v[190:193], v[82:85]
	v_mfma_f32_16x16x32_bf16 v[74:77], v[138:141], v[186:189], v[74:77]
	v_mfma_f32_16x16x32_bf16 v[74:77], v[142:145], v[190:193], v[74:77]
	s_setprio 0
	s_setprio 1
	v_mfma_f32_16x16x32_bf16 v[118:121], v[146:149], v[162:165], v[118:121]
	v_mfma_f32_16x16x32_bf16 v[118:121], v[150:153], v[166:169], v[118:121]
	v_mfma_f32_16x16x32_bf16 v[110:113], v[154:157], v[162:165], v[110:113]
	v_mfma_f32_16x16x32_bf16 v[110:113], v[158:161], v[166:169], v[110:113]
	v_mfma_f32_16x16x32_bf16 v[102:105], v[146:149], v[170:173], v[102:105]
	v_mfma_f32_16x16x32_bf16 v[102:105], v[150:153], v[174:177], v[102:105]
	v_mfma_f32_16x16x32_bf16 v[94:97], v[154:157], v[170:173], v[94:97]
	v_mfma_f32_16x16x32_bf16 v[94:97], v[158:161], v[174:177], v[94:97]
	v_mfma_f32_16x16x32_bf16 v[86:89], v[146:149], v[178:181], v[86:89]
	v_mfma_f32_16x16x32_bf16 v[86:89], v[150:153], v[182:185], v[86:89]
	v_mfma_f32_16x16x32_bf16 v[78:81], v[154:157], v[178:181], v[78:81]
	v_mfma_f32_16x16x32_bf16 v[78:81], v[158:161], v[182:185], v[78:81]
	s_setprio 3
	s_barrier
	v_mfma_f32_16x16x32_bf16 v[70:73], v[146:149], v[186:189], v[70:73]
	v_mfma_f32_16x16x32_bf16 v[70:73], v[150:153], v[190:193], v[70:73]
	v_mfma_f32_16x16x32_bf16 v[66:69], v[154:157], v[186:189], v[66:69]
	v_mfma_f32_16x16x32_bf16 v[66:69], v[158:161], v[190:193], v[66:69]
	s_setprio 0
	s_add_i32 s35, s35, s19
	s_mov_b32 m0, s35
	ds_read_b128 v[162:165], v245 offset:49152
	ds_read_b128 v[166:169], v245 offset:50176
	ds_read_b128 v[170:173], v245 offset:51200
	ds_read_b128 v[174:177], v245 offset:52224
	ds_read_b128 v[178:181], v245 offset:53248
	ds_read_b128 v[182:185], v245 offset:54272
	ds_read_b128 v[186:189], v245 offset:55296
	ds_read_b128 v[190:193], v245 offset:56320
	global_load_lds_dwordx4 v0, s[98:99]
	s_add_i32 m0, s35, 0x2000
	s_add_i32 s35, s84, s19
	global_load_lds_dwordx4 v222, s[98:99]
	s_add_u32 s98, s98, s2
	s_addc_u32 s99, s99, 0
	s_mov_b32 m0, s35
	s_nop 0
	global_load_lds_dwordx4 v0, s[98:99]
	s_add_i32 m0, s35, 0x2000
	s_nop 0
	global_load_lds_dwordx4 v222, s[98:99]
	s_mov_b32 m0, s37
	s_nop 0
	global_load_lds_dwordx4 v0, s[100:101]
	s_mov_b32 m0, s40
	s_nop 0
	global_load_lds_dwordx4 v222, s[100:101]
	s_waitcnt vmcnt(8)
	s_waitcnt lgkmcnt(0)
	s_barrier
	s_setprio 1
	s_waitcnt lgkmcnt(0)
	v_mfma_f32_16x16x32_bf16 v[62:65], v[130:133], v[162:165], v[62:65]
	v_mfma_f32_16x16x32_bf16 v[62:65], v[134:137], v[166:169], v[62:65]
	v_mfma_f32_16x16x32_bf16 v[58:61], v[138:141], v[162:165], v[58:61]
	v_mfma_f32_16x16x32_bf16 v[58:61], v[142:145], v[166:169], v[58:61]
	v_mfma_f32_16x16x32_bf16 v[50:53], v[130:133], v[170:173], v[50:53]
	v_mfma_f32_16x16x32_bf16 v[50:53], v[134:137], v[174:177], v[50:53]
	v_mfma_f32_16x16x32_bf16 v[42:45], v[138:141], v[170:173], v[42:45]
	v_mfma_f32_16x16x32_bf16 v[42:45], v[142:145], v[174:177], v[42:45]
	v_mfma_f32_16x16x32_bf16 v[34:37], v[130:133], v[178:181], v[34:37]
	v_mfma_f32_16x16x32_bf16 v[34:37], v[134:137], v[182:185], v[34:37]
	v_mfma_f32_16x16x32_bf16 v[26:29], v[138:141], v[178:181], v[26:29]
	v_mfma_f32_16x16x32_bf16 v[26:29], v[142:145], v[182:185], v[26:29]
	v_mfma_f32_16x16x32_bf16 v[18:21], v[130:133], v[186:189], v[18:21]
	v_mfma_f32_16x16x32_bf16 v[18:21], v[134:137], v[190:193], v[18:21]
	v_mfma_f32_16x16x32_bf16 v[10:13], v[138:141], v[186:189], v[10:13]
	v_mfma_f32_16x16x32_bf16 v[10:13], v[142:145], v[190:193], v[10:13]
	s_setprio 0
	s_setprio 1
	v_mfma_f32_16x16x32_bf16 v[54:57], v[146:149], v[162:165], v[54:57]
	v_mfma_f32_16x16x32_bf16 v[54:57], v[150:153], v[166:169], v[54:57]
	v_mfma_f32_16x16x32_bf16 v[46:49], v[154:157], v[162:165], v[46:49]
	v_mfma_f32_16x16x32_bf16 v[46:49], v[158:161], v[166:169], v[46:49]
	v_mfma_f32_16x16x32_bf16 v[38:41], v[146:149], v[170:173], v[38:41]
	v_mfma_f32_16x16x32_bf16 v[38:41], v[150:153], v[174:177], v[38:41]
	v_mfma_f32_16x16x32_bf16 v[30:33], v[154:157], v[170:173], v[30:33]
	v_mfma_f32_16x16x32_bf16 v[30:33], v[158:161], v[174:177], v[30:33]
	v_mfma_f32_16x16x32_bf16 v[22:25], v[146:149], v[178:181], v[22:25]
	v_mfma_f32_16x16x32_bf16 v[22:25], v[150:153], v[182:185], v[22:25]
	v_mfma_f32_16x16x32_bf16 v[14:17], v[154:157], v[178:181], v[14:17]
	v_mfma_f32_16x16x32_bf16 v[14:17], v[158:161], v[182:185], v[14:17]
	s_setprio 3
	s_barrier
	v_mfma_f32_16x16x32_bf16 v[6:9], v[146:149], v[186:189], v[6:9]
	v_mfma_f32_16x16x32_bf16 v[6:9], v[150:153], v[190:193], v[6:9]
	v_mfma_f32_16x16x32_bf16 v[2:5], v[154:157], v[186:189], v[2:5]
	v_mfma_f32_16x16x32_bf16 v[2:5], v[158:161], v[190:193], v[2:5]
	s_setprio 0
	s_add_u32 s0, s0, 0x100
	s_addc_u32 s1, s1, 0
	s_add_u32 vcc_lo, vcc_lo, 0x100
	s_addc_u32 vcc_hi, vcc_hi, 0
	s_cmp_ge_u32 s34, s18
	s_mov_b32 s68, s34
	s_cbranch_scc0 .LBB0_707
	s_and_b64 vcc, exec, s[50:51]
	s_cbranch_vccz .LBB0_710
	s_barrier
